# scan step loop: latch moved to the bottom (single conditional back edge per step instead of two taken branches)
# baseline (speedup 1.0000x reference)
; #define LAS __attribute__((address_space(3)))
; __device__ __forceinline__ void even_scan(const Params& p, int j, LAS unsigned char* lds, int gw, int NGW, int wave, int lane) {
;     ...
;             LAS float* bb = buf + (st & 1) * (TS * 384);
; #pragma unroll 1
;             for (int s = 0; s < TS; ++s) {
;                 const LAS float* sb = bb + s * 384 + cq * 16;
;                 f32x4 cbuf[CPS];
; #pragma unroll
;                 for (int c = 0; c < CPS; ++c) { const int li = cli + c * NGW * 64;
;                     if (li < KVC_N2 && ((li >> 8) & 2047) >= 8) cbuf[c] = __builtin_nontemporal_load(csrc + c * NGW * 64); }
.LBB0_1329:
	v_readlane_b32 s24, v254, 57
	v_readlane_b32 s25, v254, 58
	s_bitcmp1_b32 s12, 0
	s_cselect_b32 s12, 0x1800, 0
	v_lshl_add_u64 v[210:211], v[192:193], 0, s[24:25]
	v_readlane_b32 s24, v254, 59
	v_readlane_b32 s25, v254, 60
	v_add_u32_e32 v184, s12, v203
	v_add_u32_e32 v234, s12, v233
	v_lshl_add_u64 v[162:163], v[192:193], 0, s[24:25]
	v_readlane_b32 s24, v254, 61
	v_readlane_b32 s25, v254, 62
	v_lshl_add_u64 v[212:213], v[162:163], 0, s[60:61]
	s_mov_b64 s[38:39], 0
	v_lshl_add_u64 v[162:163], v[192:193], 0, s[24:25]
	v_lshl_add_u64 v[214:215], v[162:163], 0, s[60:61]
	s_mov_b64 s[12:13], 0
.LBB0_1331:
	v_and_b32_e32 v161, 0x7f800, v160
	v_cmp_gt_i32_e32 vcc, s4, v160
	v_cmp_ne_u32_e64 s[36:37], 0, v161
	s_and_b64 s[26:27], vcc, s[36:37]
	s_and_saveexec_b64 s[24:25], s[26:27]
	s_cbranch_execz .LBB0_1333
	v_lshl_add_u64 v[4:5], v[192:193], 0, s[12:13]
	global_load_dwordx4 v[4:7], v[4:5], off nt

; __device__ __forceinline__ void even_scan(const Params& p, int j, LAS unsigned char* lds, int gw, int NGW, int wave, int lane) {
;     ...
;                 const size_t oo = base + (size_t)(st * TS + s) * 512 + lane;
;                 YL[oo] = yoL; if (!samp) QQ[oo] = yoP;
; #pragma unroll
;                 for (int c = 0; c < CPS; ++c) { const int li = cli + c * NGW * 64;
;                     if (li < KVC_N2 && ((li >> 8) & 2047) >= 8) __builtin_nontemporal_store(cbuf[c], (f32x4*)((char*)(csrc + c * NGW * 64) + cdelta)); }
;                 cli += cstride; csrc += cstride; ++cstep;
;             }
.Lscan_stb_skip:
	s_or_b64 exec, exec, s[24:25]
	v_lshl_add_u64 v[162:163], v[206:207], 0, s[38:39]
	v_add_co_u32_e32 v162, vcc, 0x37500000, v162
	v_add_f32_e32 v160, v182, v180
	s_nop 0
	v_addc_co_u32_e32 v163, vcc, 0, v163, vcc
	s_nop 1
	v_permlane32_swap_b32 v160, v161
	global_store_dword v[162:163], v164, off
	v_cndmask_b32_e64 v162, 0, 1, s[62:63]
	v_cmp_ne_u32_e64 s[36:37], 1, v162
	s_andn2_b64 vcc, exec, s[62:63]
	s_cbranch_vccnz .Lscan_latch
	v_add_f32_e32 v162, v160, v161
	v_lshl_add_u64 v[160:161], v[208:209], 0, s[38:39]
	global_store_dword v[160:161], v162, off
.Lscan_latch:
	s_or_b64 exec, exec, s[24:25]
	s_add_u32 s12, s12, s20
	s_addc_u32 s13, s13, s21
	s_add_u32 s38, s38, 0x800
	s_addc_u32 s39, s39, 0
	v_add_u32_e32 v160, s18, v235
	v_add_u32_e32 v184, 0x600, v184
	s_cmpk_eq_i32 s38, 0x2000
	v_add_u32_e32 v234, 0x600, v234
	s_cbranch_scc0 .LBB0_1331
